# v_full3 + grid barrier: waiting workgroups poll the top-level generation word directly (one dependent hop less)
# baseline (speedup 1.0000x reference)
.LBB0_174:
	s_or_b64 exec, exec, s[6:7]
	v_cvt_f32_u32_e32 v4, v2
	s_waitcnt vmcnt(0)
	v_readfirstlane_b32 s4, v3
	v_sub_u32_e32 v3, 0, v2
	v_rcp_iflag_f32_e32 v4, v4
	v_add_u32_e32 v5, s4, v1
	v_mul_f32_e32 v4, 0x4f7ffffe, v4
	v_cvt_u32_f32_e32 v4, v4
	v_mul_lo_u32 v1, v3, v4
	v_mul_hi_u32 v1, v4, v1
	v_add_u32_e32 v1, v4, v1
	v_mul_hi_u32 v1, v5, v1
	v_mul_lo_u32 v3, v1, v2
	v_sub_u32_e32 v3, v5, v3
	v_add_u32_e32 v4, 1, v1
	v_cmp_ge_u32_e32 vcc, v3, v2
	s_nop 1
	v_cndmask_b32_e32 v1, v1, v4, vcc
	v_sub_u32_e32 v4, v3, v2
	v_cndmask_b32_e32 v3, v3, v4, vcc
	v_add_u32_e32 v4, 1, v1
	v_cmp_ge_u32_e32 vcc, v3, v2
	v_add_u32_e32 v3, 1, v5
	s_nop 0
	v_cndmask_b32_e32 v1, v1, v4, vcc
	v_mul_lo_u32 v4, v2, v1
	v_add_u32_e32 v2, v4, v2
	v_cmp_ne_u32_e32 vcc, v3, v2
	s_and_saveexec_b64 s[4:5], vcc
	s_xor_b64 s[4:5], exec, s[4:5]
	s_cbranch_execz .LBB0_188
	s_waitcnt lgkmcnt(0)
	v_mov_b32_e32 v0, 0
	v_readlane_b32 s10, v253, 12
	v_readlane_b32 s11, v253, 13
	s_nop 0
	s_add_u32 s10, s10, 0x3500
	s_addc_u32 s11, s11, 0
	s_nop 1
	global_load_dword v0, v0, s[10:11] sc1
	s_waitcnt vmcnt(0)
	v_cmp_eq_u32_e32 vcc, v0, v1
	s_and_saveexec_b64 s[6:7], vcc
	s_cbranch_execz .LBB0_187
	s_add_u32 s8, s78, 0x1d4b9600
	s_addc_u32 s9, s79, 0
	s_mov_b32 s14, 1
	s_mov_b64 s[12:13], 0
	v_mov_b32_e32 v0, 0
	s_branch .LBB0_178

.LBB0_250:
	s_or_b64 exec, exec, s[6:7]
	v_cvt_f32_u32_e32 v4, v2
	s_waitcnt vmcnt(0)
	v_readfirstlane_b32 s4, v3
	v_sub_u32_e32 v3, 0, v2
	v_rcp_iflag_f32_e32 v4, v4
	v_add_u32_e32 v5, s4, v1
	v_mul_f32_e32 v4, 0x4f7ffffe, v4
	v_cvt_u32_f32_e32 v4, v4
	v_mul_lo_u32 v1, v3, v4
	v_mul_hi_u32 v1, v4, v1
	v_add_u32_e32 v1, v4, v1
	v_mul_hi_u32 v1, v5, v1
	v_mul_lo_u32 v3, v1, v2
	v_sub_u32_e32 v3, v5, v3
	v_add_u32_e32 v4, 1, v1
	v_cmp_ge_u32_e32 vcc, v3, v2
	s_nop 1
	v_cndmask_b32_e32 v1, v1, v4, vcc
	v_sub_u32_e32 v4, v3, v2
	v_cndmask_b32_e32 v3, v3, v4, vcc
	v_add_u32_e32 v4, 1, v1
	v_cmp_ge_u32_e32 vcc, v3, v2
	v_add_u32_e32 v3, 1, v5
	s_nop 0
	v_cndmask_b32_e32 v1, v1, v4, vcc
	v_mul_lo_u32 v4, v2, v1
	v_add_u32_e32 v2, v4, v2
	v_cmp_ne_u32_e32 vcc, v3, v2
	s_and_saveexec_b64 s[4:5], vcc
	s_xor_b64 s[4:5], exec, s[4:5]
	s_cbranch_execz .LBB0_264
	s_waitcnt lgkmcnt(0)
	v_readlane_b32 s8, v253, 12
	v_readlane_b32 s9, v253, 13
	s_nop 0
	s_add_u32 s8, s8, 0x3500
	s_addc_u32 s9, s9, 0
	s_nop 1
	global_load_dword v0, v113, s[8:9] sc1
	s_waitcnt vmcnt(0)
	v_cmp_eq_u32_e32 vcc, v0, v1
	s_and_saveexec_b64 s[6:7], vcc
	s_cbranch_execz .LBB0_263
	s_mov_b32 s10, 1
	s_mov_b64 s[12:13], 0
	s_branch .LBB0_254
